# FFN-up tail round split into half units over 44 workgroups (separate K-loop copy, hand-written half epilogue)
# baseline (speedup 1.0000x reference)
.LBB0_1481:
	s_ashr_i32 s25, s24, 31
	s_lshl_b64 s[26:27], s[24:25], 19
	s_add_u32 s26, s38, s26
	s_addc_u32 s27, s39, s27
	s_and_b64 s[28:29], s[6:7], exec
	s_cselect_b32 s25, s27, s31
	s_cselect_b32 s58, s26, s30
	s_ashr_i32 s23, s22, 31
	s_lshl_b64 s[28:29], s[22:23], 19
	s_add_u32 s28, s40, s28
	s_addc_u32 s29, s41, s29
	s_and_b64 s[36:37], s[6:7], exec
	s_cselect_b32 s23, s29, s35
	s_cselect_b32 s59, s28, s34
	s_add_u32 s30, s30, 0x40080
	s_addc_u32 s31, s31, 0
	s_add_u32 s63, s34, 0x100
	v_mov_b32_e32 v0, 0
	s_addc_u32 s64, s35, 0
	s_mov_b32 s65, -2
	v_mov_b32_e32 v1, v0
	v_mov_b32_e32 v2, v0
	v_mov_b32_e32 v3, v0
	v_mov_b32_e32 v4, v0
	v_mov_b32_e32 v5, v0
	v_mov_b32_e32 v6, v0
	v_mov_b32_e32 v7, v0
	v_mov_b32_e32 v16, v0
	v_mov_b32_e32 v17, v0
	v_mov_b32_e32 v18, v0
	v_mov_b32_e32 v19, v0
	v_mov_b32_e32 v20, v0
	v_mov_b32_e32 v21, v0
	v_mov_b32_e32 v22, v0
	v_mov_b32_e32 v23, v0
	v_mov_b32_e32 v32, v0
	v_mov_b32_e32 v33, v0
	v_mov_b32_e32 v34, v0
	v_mov_b32_e32 v35, v0
	v_mov_b32_e32 v36, v0
	v_mov_b32_e32 v37, v0
	v_mov_b32_e32 v38, v0
	v_mov_b32_e32 v39, v0
	v_mov_b32_e32 v48, v0
	v_mov_b32_e32 v49, v0
	v_mov_b32_e32 v50, v0
	v_mov_b32_e32 v51, v0
	v_mov_b32_e32 v52, v0
	v_mov_b32_e32 v53, v0
	v_mov_b32_e32 v54, v0
	v_mov_b32_e32 v55, v0
	v_mov_b32_e32 v8, v0
	v_mov_b32_e32 v9, v0
	v_mov_b32_e32 v10, v0
	v_mov_b32_e32 v11, v0
	v_mov_b32_e32 v12, v0
	v_mov_b32_e32 v13, v0
	v_mov_b32_e32 v14, v0
	v_mov_b32_e32 v15, v0
	v_mov_b32_e32 v24, v0
	v_mov_b32_e32 v25, v0
	v_mov_b32_e32 v26, v0
	v_mov_b32_e32 v27, v0
	v_mov_b32_e32 v28, v0
	v_mov_b32_e32 v29, v0
	v_mov_b32_e32 v30, v0
	v_mov_b32_e32 v31, v0
	v_mov_b32_e32 v40, v0
	v_mov_b32_e32 v41, v0
	v_mov_b32_e32 v42, v0
	v_mov_b32_e32 v43, v0
	v_mov_b32_e32 v44, v0
	v_mov_b32_e32 v45, v0
	v_mov_b32_e32 v46, v0
	v_mov_b32_e32 v47, v0
	v_mov_b32_e32 v56, v0
	v_mov_b32_e32 v57, v0
	v_mov_b32_e32 v58, v0
	v_mov_b32_e32 v59, v0
	v_mov_b32_e32 v60, v0
	v_mov_b32_e32 v61, v0
	v_mov_b32_e32 v62, v0
	v_mov_b32_e32 v63, v0
	v_mov_b32_e32 v64, v0
	v_mov_b32_e32 v65, v0
	v_mov_b32_e32 v66, v0
	v_mov_b32_e32 v67, v0
	v_mov_b32_e32 v68, v0
	v_mov_b32_e32 v69, v0
	v_mov_b32_e32 v70, v0
	v_mov_b32_e32 v71, v0
	v_mov_b32_e32 v80, v0
	v_mov_b32_e32 v81, v0
	v_mov_b32_e32 v82, v0
	v_mov_b32_e32 v83, v0
	v_mov_b32_e32 v84, v0
	v_mov_b32_e32 v85, v0
	v_mov_b32_e32 v86, v0
	v_mov_b32_e32 v87, v0
	v_mov_b32_e32 v96, v0
	v_mov_b32_e32 v97, v0
	v_mov_b32_e32 v98, v0
	v_mov_b32_e32 v99, v0
	v_mov_b32_e32 v100, v0
	v_mov_b32_e32 v101, v0
	v_mov_b32_e32 v102, v0
	v_mov_b32_e32 v103, v0
	v_mov_b32_e32 v112, v0
	v_mov_b32_e32 v113, v0
	v_mov_b32_e32 v114, v0
	v_mov_b32_e32 v115, v0
	v_mov_b32_e32 v116, v0
	v_mov_b32_e32 v117, v0
	v_mov_b32_e32 v118, v0
	v_mov_b32_e32 v119, v0
	v_mov_b32_e32 v72, v0
	v_mov_b32_e32 v73, v0
	v_mov_b32_e32 v74, v0
	v_mov_b32_e32 v75, v0
	v_mov_b32_e32 v76, v0
	v_mov_b32_e32 v77, v0
	v_mov_b32_e32 v78, v0
	v_mov_b32_e32 v79, v0
	v_mov_b32_e32 v88, v0
	v_mov_b32_e32 v89, v0
	v_mov_b32_e32 v90, v0
	v_mov_b32_e32 v91, v0
	v_mov_b32_e32 v92, v0
	v_mov_b32_e32 v93, v0
	v_mov_b32_e32 v94, v0
	v_mov_b32_e32 v95, v0
	v_mov_b32_e32 v104, v0
	v_mov_b32_e32 v105, v0
	v_mov_b32_e32 v106, v0
	v_mov_b32_e32 v107, v0
	v_mov_b32_e32 v108, v0
	v_mov_b32_e32 v109, v0
	v_mov_b32_e32 v110, v0
	v_mov_b32_e32 v111, v0
	v_mov_b32_e32 v120, v0
	v_mov_b32_e32 v121, v0
	v_mov_b32_e32 v122, v0
	v_mov_b32_e32 v123, v0
	v_mov_b32_e32 v124, v0
	v_mov_b32_e32 v125, v0
	v_mov_b32_e32 v126, v0
	v_mov_b32_e32 v127, v0
	s_branch .Lhk_skip_7

.Lmf_7_7:
	s_setprio 0
	s_barrier
	s_add_i32 s65, s65, 2
	s_add_u32 s30, s30, 0x100
	s_addc_u32 s31, s31, 0
	s_add_u32 s63, s63, 0x100
	s_addc_u32 s64, s64, 0
	s_cmp_gt_u32 s65, 13
	s_cbranch_scc0 .Lhk_7
	s_branch .Lhk_join_7
.Lhk_skip_7:
	s_bitcmp1_b32 s101, 6
	s_cbranch_scc1 .Lhk_7
.LBB0_1482:
	ds_read_b128 v[144:147], v155
	ds_read_b128 v[148:151], v155 offset:1024
	ds_read_b128 v[160:163], v155 offset:2048
	ds_read_b128 v[164:167], v155 offset:3072
	ds_read_b128 v[168:171], v156
	ds_read_b128 v[172:175], v156 offset:1024
	ds_read_b128 v[176:179], v156 offset:2048
	ds_read_b128 v[182:185], v156 offset:3072
	s_add_u32 s34, s30, 0xfffc0080
	s_addc_u32 s35, s31, -1
	s_cmp_eq_u32 s65, 12
	s_cselect_b32 s37, s25, s35
	s_cselect_b32 s36, s58, s34
	s_cselect_b32 s35, s23, s64
	s_cselect_b32 s34, s59, s63
	v_lshl_add_u64 v[152:153], s[30:31], 0, v[136:137]
	s_add_i32 m0, s43, 0xc000
	ds_read_b128 v[186:189], v157
	ds_read_b128 v[190:193], v157 offset:1024
	ds_read_b128 v[194:197], v157 offset:2048
	ds_read_b128 v[198:201], v157 offset:3072
	ds_read_b128 v[202:205], v157 offset:4096
	ds_read_b128 v[206:209], v157 offset:5120
	ds_read_b128 v[210:213], v157 offset:6144
	ds_read_b128 v[214:217], v157 offset:7168
	global_load_lds_dwordx4 v[152:153], off
	v_lshl_add_u64 v[152:153], s[30:31], 0, v[138:139]
	s_add_i32 m0, s43, 0xe000
	s_nop 0
	global_load_lds_dwordx4 v[152:153], off
	s_waitcnt vmcnt(8)
	s_waitcnt lgkmcnt(0)
	s_barrier
	s_setprio 1
	s_waitcnt lgkmcnt(0)
	v_mfma_f32_16x16x32_bf16 v[124:127], v[144:147], v[186:189], v[124:127]
	v_mfma_f32_16x16x32_bf16 v[120:123], v[160:163], v[186:189], v[120:123]
	v_mfma_f32_16x16x32_bf16 v[108:111], v[144:147], v[194:197], v[108:111]
	v_mfma_f32_16x16x32_bf16 v[104:107], v[160:163], v[194:197], v[104:107]
	v_mfma_f32_16x16x32_bf16 v[92:95], v[144:147], v[202:205], v[92:95]
	v_mfma_f32_16x16x32_bf16 v[88:91], v[160:163], v[202:205], v[88:91]
	v_mfma_f32_16x16x32_bf16 v[76:79], v[144:147], v[210:213], v[76:79]
	v_mfma_f32_16x16x32_bf16 v[72:75], v[160:163], v[210:213], v[72:75]
	v_mfma_f32_16x16x32_bf16 v[124:127], v[148:151], v[190:193], v[124:127]
	v_mfma_f32_16x16x32_bf16 v[120:123], v[164:167], v[190:193], v[120:123]
	v_mfma_f32_16x16x32_bf16 v[108:111], v[148:151], v[198:201], v[108:111]
	v_mfma_f32_16x16x32_bf16 v[104:107], v[164:167], v[198:201], v[104:107]
	v_mfma_f32_16x16x32_bf16 v[92:95], v[148:151], v[206:209], v[92:95]
	v_mfma_f32_16x16x32_bf16 v[88:91], v[164:167], v[206:209], v[88:91]
	v_mfma_f32_16x16x32_bf16 v[76:79], v[148:151], v[214:217], v[76:79]
	v_mfma_f32_16x16x32_bf16 v[72:75], v[164:167], v[214:217], v[72:75]
	s_setprio 0
	s_setprio 1
	v_mfma_f32_16x16x32_bf16 v[116:119], v[168:171], v[186:189], v[116:119]
	v_mfma_f32_16x16x32_bf16 v[112:115], v[176:179], v[186:189], v[112:115]
	v_mfma_f32_16x16x32_bf16 v[100:103], v[168:171], v[194:197], v[100:103]
	v_mfma_f32_16x16x32_bf16 v[96:99], v[176:179], v[194:197], v[96:99]
	v_mfma_f32_16x16x32_bf16 v[84:87], v[168:171], v[202:205], v[84:87]
	v_mfma_f32_16x16x32_bf16 v[80:83], v[176:179], v[202:205], v[80:83]
	v_mfma_f32_16x16x32_bf16 v[68:71], v[168:171], v[210:213], v[68:71]
	v_mfma_f32_16x16x32_bf16 v[64:67], v[176:179], v[210:213], v[64:67]
	v_mfma_f32_16x16x32_bf16 v[116:119], v[172:175], v[190:193], v[116:119]
	v_mfma_f32_16x16x32_bf16 v[112:115], v[182:185], v[190:193], v[112:115]
	v_mfma_f32_16x16x32_bf16 v[100:103], v[172:175], v[198:201], v[100:103]
	v_mfma_f32_16x16x32_bf16 v[96:99], v[182:185], v[198:201], v[96:99]
	v_mfma_f32_16x16x32_bf16 v[84:87], v[172:175], v[206:209], v[84:87]
	v_mfma_f32_16x16x32_bf16 v[80:83], v[182:185], v[206:209], v[80:83]
	v_mfma_f32_16x16x32_bf16 v[68:71], v[172:175], v[214:217], v[68:71]
	v_mfma_f32_16x16x32_bf16 v[64:67], v[182:185], v[214:217], v[64:67]
	s_setprio 0
	s_barrier
	s_add_i32 s66, s54, s42
	v_lshl_add_u64 v[152:153], s[34:35], 0, v[132:133]
	s_mov_b32 m0, s66
	ds_read_b128 v[186:189], v157 offset:16384
	ds_read_b128 v[190:193], v157 offset:17408
	ds_read_b128 v[194:197], v157 offset:18432
	ds_read_b128 v[198:201], v157 offset:19456
	ds_read_b128 v[202:205], v157 offset:20480
	ds_read_b128 v[206:209], v157 offset:21504
	ds_read_b128 v[210:213], v157 offset:22528
	ds_read_b128 v[214:217], v157 offset:23552
	global_load_lds_dwordx4 v[152:153], off
	s_add_i32 m0, s66, 0x2000
	s_add_u32 s66, s34, 0x40000
	v_lshl_add_u64 v[218:219], s[34:35], 0, v[128:129]
	s_addc_u32 s67, s35, 0
	s_add_i32 s68, s55, s42
	global_load_lds_dwordx4 v[218:219], off
	v_lshl_add_u64 v[220:221], s[66:67], 0, v[132:133]
	s_mov_b32 m0, s68
	v_lshl_add_u64 v[222:223], s[36:37], 0, v[130:131]
	global_load_lds_dwordx4 v[220:221], off
	v_lshl_add_u64 v[220:221], s[66:67], 0, v[128:129]
	s_add_i32 m0, s68, 0x2000
	s_nop 0
	global_load_lds_dwordx4 v[220:221], off
	v_lshl_add_u64 v[220:221], s[36:37], 0, v[134:135]
	s_mov_b32 m0, s43
	s_nop 0
	global_load_lds_dwordx4 v[220:221], off
	s_mov_b32 m0, s44
	s_nop 0
	global_load_lds_dwordx4 v[222:223], off
	s_waitcnt vmcnt(8)
	s_waitcnt lgkmcnt(0)
	s_barrier
	s_setprio 1
	s_waitcnt lgkmcnt(0)
	v_mfma_f32_16x16x32_bf16 v[60:63], v[144:147], v[186:189], v[60:63]
	v_mfma_f32_16x16x32_bf16 v[56:59], v[160:163], v[186:189], v[56:59]
	v_mfma_f32_16x16x32_bf16 v[44:47], v[144:147], v[194:197], v[44:47]
	v_mfma_f32_16x16x32_bf16 v[40:43], v[160:163], v[194:197], v[40:43]
	v_mfma_f32_16x16x32_bf16 v[28:31], v[144:147], v[202:205], v[28:31]
	v_mfma_f32_16x16x32_bf16 v[24:27], v[160:163], v[202:205], v[24:27]
	v_mfma_f32_16x16x32_bf16 v[12:15], v[144:147], v[210:213], v[12:15]
	v_mfma_f32_16x16x32_bf16 v[8:11], v[160:163], v[210:213], v[8:11]
	v_mfma_f32_16x16x32_bf16 v[60:63], v[148:151], v[190:193], v[60:63]
	v_mfma_f32_16x16x32_bf16 v[56:59], v[164:167], v[190:193], v[56:59]
	v_mfma_f32_16x16x32_bf16 v[44:47], v[148:151], v[198:201], v[44:47]
	v_mfma_f32_16x16x32_bf16 v[40:43], v[164:167], v[198:201], v[40:43]
	v_mfma_f32_16x16x32_bf16 v[28:31], v[148:151], v[206:209], v[28:31]
	v_mfma_f32_16x16x32_bf16 v[24:27], v[164:167], v[206:209], v[24:27]
	v_mfma_f32_16x16x32_bf16 v[12:15], v[148:151], v[214:217], v[12:15]
	v_mfma_f32_16x16x32_bf16 v[8:11], v[164:167], v[214:217], v[8:11]
	s_setprio 0
	s_setprio 1
	v_mfma_f32_16x16x32_bf16 v[52:55], v[168:171], v[186:189], v[52:55]
	v_mfma_f32_16x16x32_bf16 v[48:51], v[176:179], v[186:189], v[48:51]
	v_mfma_f32_16x16x32_bf16 v[36:39], v[168:171], v[194:197], v[36:39]
	v_mfma_f32_16x16x32_bf16 v[32:35], v[176:179], v[194:197], v[32:35]
	v_mfma_f32_16x16x32_bf16 v[20:23], v[168:171], v[202:205], v[20:23]
	v_mfma_f32_16x16x32_bf16 v[16:19], v[176:179], v[202:205], v[16:19]
	v_mfma_f32_16x16x32_bf16 v[4:7], v[168:171], v[210:213], v[4:7]
	v_mfma_f32_16x16x32_bf16 v[0:3], v[176:179], v[210:213], v[0:3]
	v_mfma_f32_16x16x32_bf16 v[52:55], v[172:175], v[190:193], v[52:55]
	v_mfma_f32_16x16x32_bf16 v[48:51], v[182:185], v[190:193], v[48:51]
	v_mfma_f32_16x16x32_bf16 v[36:39], v[172:175], v[198:201], v[36:39]
	v_mfma_f32_16x16x32_bf16 v[32:35], v[182:185], v[198:201], v[32:35]
	v_mfma_f32_16x16x32_bf16 v[20:23], v[172:175], v[206:209], v[20:23]
	v_mfma_f32_16x16x32_bf16 v[16:19], v[182:185], v[206:209], v[16:19]
	v_mfma_f32_16x16x32_bf16 v[4:7], v[172:175], v[214:217], v[4:7]
	v_mfma_f32_16x16x32_bf16 v[0:3], v[182:185], v[214:217], v[0:3]
	s_setprio 0
	s_barrier
	s_add_i32 s66, 0, 0x18000
	v_add_u32_e32 v159, s66, v154
	s_add_i32 s67, 0, 0x1c000
	ds_read_b128 v[144:147], v159
	ds_read_b128 v[148:151], v159 offset:1024
	ds_read_b128 v[160:163], v159 offset:2048
	ds_read_b128 v[164:167], v159 offset:3072
	v_add_u32_e32 v159, s67, v154
	ds_read_b128 v[168:171], v159
	ds_read_b128 v[172:175], v159 offset:1024
	ds_read_b128 v[176:179], v159 offset:2048
	ds_read_b128 v[182:185], v159 offset:3072
	s_add_u32 s36, s36, 0x40000
	s_addc_u32 s37, s37, 0
	s_mov_b32 m0, s45
	v_lshl_add_u64 v[224:225], s[36:37], 0, v[134:135]
	ds_read_b128 v[186:189], v157 offset:32768
	ds_read_b128 v[190:193], v157 offset:33792
	ds_read_b128 v[194:197], v157 offset:34816
	ds_read_b128 v[198:201], v157 offset:35840
	ds_read_b128 v[202:205], v157 offset:36864
	ds_read_b128 v[206:209], v157 offset:37888
	ds_read_b128 v[210:213], v157 offset:38912
	ds_read_b128 v[214:217], v157 offset:39936
	global_load_lds_dwordx4 v[224:225], off
	v_lshl_add_u64 v[224:225], s[36:37], 0, v[130:131]
	s_mov_b32 m0, s48
	s_nop 0
	global_load_lds_dwordx4 v[224:225], off
	s_waitcnt vmcnt(8)
	s_waitcnt lgkmcnt(0)
	s_barrier
	s_setprio 1
	s_waitcnt lgkmcnt(0)
	v_mfma_f32_16x16x32_bf16 v[124:127], v[144:147], v[186:189], v[124:127]
	v_mfma_f32_16x16x32_bf16 v[120:123], v[160:163], v[186:189], v[120:123]
	v_mfma_f32_16x16x32_bf16 v[108:111], v[144:147], v[194:197], v[108:111]
	v_mfma_f32_16x16x32_bf16 v[104:107], v[160:163], v[194:197], v[104:107]
	v_mfma_f32_16x16x32_bf16 v[92:95], v[144:147], v[202:205], v[92:95]
	v_mfma_f32_16x16x32_bf16 v[88:91], v[160:163], v[202:205], v[88:91]
	v_mfma_f32_16x16x32_bf16 v[76:79], v[144:147], v[210:213], v[76:79]
	v_mfma_f32_16x16x32_bf16 v[72:75], v[160:163], v[210:213], v[72:75]
	v_mfma_f32_16x16x32_bf16 v[124:127], v[148:151], v[190:193], v[124:127]
	v_mfma_f32_16x16x32_bf16 v[120:123], v[164:167], v[190:193], v[120:123]
	v_mfma_f32_16x16x32_bf16 v[108:111], v[148:151], v[198:201], v[108:111]
	v_mfma_f32_16x16x32_bf16 v[104:107], v[164:167], v[198:201], v[104:107]
	v_mfma_f32_16x16x32_bf16 v[92:95], v[148:151], v[206:209], v[92:95]
	v_mfma_f32_16x16x32_bf16 v[88:91], v[164:167], v[206:209], v[88:91]
	v_mfma_f32_16x16x32_bf16 v[76:79], v[148:151], v[214:217], v[76:79]
	v_mfma_f32_16x16x32_bf16 v[72:75], v[164:167], v[214:217], v[72:75]
	s_setprio 0
	s_setprio 1
	v_mfma_f32_16x16x32_bf16 v[116:119], v[168:171], v[186:189], v[116:119]
	v_mfma_f32_16x16x32_bf16 v[112:115], v[176:179], v[186:189], v[112:115]
	v_mfma_f32_16x16x32_bf16 v[100:103], v[168:171], v[194:197], v[100:103]
	v_mfma_f32_16x16x32_bf16 v[96:99], v[176:179], v[194:197], v[96:99]
	v_mfma_f32_16x16x32_bf16 v[84:87], v[168:171], v[202:205], v[84:87]
	v_mfma_f32_16x16x32_bf16 v[80:83], v[176:179], v[202:205], v[80:83]
	v_mfma_f32_16x16x32_bf16 v[68:71], v[168:171], v[210:213], v[68:71]
	v_mfma_f32_16x16x32_bf16 v[64:67], v[176:179], v[210:213], v[64:67]
	v_mfma_f32_16x16x32_bf16 v[116:119], v[172:175], v[190:193], v[116:119]
	v_mfma_f32_16x16x32_bf16 v[112:115], v[182:185], v[190:193], v[112:115]
	v_mfma_f32_16x16x32_bf16 v[100:103], v[172:175], v[198:201], v[100:103]
	v_mfma_f32_16x16x32_bf16 v[96:99], v[182:185], v[198:201], v[96:99]
	v_mfma_f32_16x16x32_bf16 v[84:87], v[172:175], v[206:209], v[84:87]
	v_mfma_f32_16x16x32_bf16 v[80:83], v[182:185], v[206:209], v[80:83]
	v_mfma_f32_16x16x32_bf16 v[68:71], v[172:175], v[214:217], v[68:71]
	v_mfma_f32_16x16x32_bf16 v[64:67], v[182:185], v[214:217], v[64:67]
	s_setprio 0
	s_barrier
	s_add_i32 s36, s66, s42
	v_lshl_add_u64 v[152:153], v[152:153], 0, s[18:19]
	s_mov_b32 m0, s36
	ds_read_b128 v[186:189], v157 offset:49152
	ds_read_b128 v[190:193], v157 offset:50176
	ds_read_b128 v[194:197], v157 offset:51200
	ds_read_b128 v[198:201], v157 offset:52224
	ds_read_b128 v[202:205], v157 offset:53248
	ds_read_b128 v[206:209], v157 offset:54272
	ds_read_b128 v[210:213], v157 offset:55296
	ds_read_b128 v[214:217], v157 offset:56320
	global_load_lds_dwordx4 v[152:153], off
	s_add_i32 m0, s36, 0x2000
	s_add_u32 s34, s34, 0x40080
	v_lshl_add_u64 v[152:153], v[218:219], 0, s[18:19]
	s_addc_u32 s35, s35, 0
	s_add_i32 s36, s67, s42
	global_load_lds_dwordx4 v[152:153], off
	v_lshl_add_u64 v[152:153], s[34:35], 0, v[132:133]
	s_mov_b32 m0, s36
	s_nop 0
	global_load_lds_dwordx4 v[152:153], off
	v_lshl_add_u64 v[152:153], s[34:35], 0, v[128:129]
	s_add_i32 m0, s36, 0x2000
	s_nop 0
	global_load_lds_dwordx4 v[152:153], off
	v_lshl_add_u64 v[152:153], v[220:221], 0, s[18:19]
	s_mov_b32 m0, s52
	s_nop 0
	global_load_lds_dwordx4 v[152:153], off
	v_lshl_add_u64 v[152:153], v[222:223], 0, s[18:19]
	s_mov_b32 m0, s53
	s_nop 0
	global_load_lds_dwordx4 v[152:153], off
	s_waitcnt vmcnt(8)
	s_waitcnt lgkmcnt(0)
	s_barrier
	s_setprio 1
	s_waitcnt lgkmcnt(0)
	v_mfma_f32_16x16x32_bf16 v[60:63], v[144:147], v[186:189], v[60:63]
	v_mfma_f32_16x16x32_bf16 v[56:59], v[160:163], v[186:189], v[56:59]
	v_mfma_f32_16x16x32_bf16 v[44:47], v[144:147], v[194:197], v[44:47]
	v_mfma_f32_16x16x32_bf16 v[40:43], v[160:163], v[194:197], v[40:43]
	v_mfma_f32_16x16x32_bf16 v[28:31], v[144:147], v[202:205], v[28:31]
	v_mfma_f32_16x16x32_bf16 v[24:27], v[160:163], v[202:205], v[24:27]
	v_mfma_f32_16x16x32_bf16 v[12:15], v[144:147], v[210:213], v[12:15]
	v_mfma_f32_16x16x32_bf16 v[8:11], v[160:163], v[210:213], v[8:11]
	v_mfma_f32_16x16x32_bf16 v[60:63], v[148:151], v[190:193], v[60:63]
	v_mfma_f32_16x16x32_bf16 v[56:59], v[164:167], v[190:193], v[56:59]
	v_mfma_f32_16x16x32_bf16 v[44:47], v[148:151], v[198:201], v[44:47]
	v_mfma_f32_16x16x32_bf16 v[40:43], v[164:167], v[198:201], v[40:43]
	v_mfma_f32_16x16x32_bf16 v[28:31], v[148:151], v[206:209], v[28:31]
	v_mfma_f32_16x16x32_bf16 v[24:27], v[164:167], v[206:209], v[24:27]
	v_mfma_f32_16x16x32_bf16 v[12:15], v[148:151], v[214:217], v[12:15]
	v_mfma_f32_16x16x32_bf16 v[8:11], v[164:167], v[214:217], v[8:11]
	s_setprio 0
	s_setprio 1
	v_mfma_f32_16x16x32_bf16 v[52:55], v[168:171], v[186:189], v[52:55]
	v_mfma_f32_16x16x32_bf16 v[48:51], v[176:179], v[186:189], v[48:51]
	v_mfma_f32_16x16x32_bf16 v[36:39], v[168:171], v[194:197], v[36:39]
	v_mfma_f32_16x16x32_bf16 v[32:35], v[176:179], v[194:197], v[32:35]
	v_mfma_f32_16x16x32_bf16 v[20:23], v[168:171], v[202:205], v[20:23]
	v_mfma_f32_16x16x32_bf16 v[16:19], v[176:179], v[202:205], v[16:19]
	v_mfma_f32_16x16x32_bf16 v[4:7], v[168:171], v[210:213], v[4:7]
	v_mfma_f32_16x16x32_bf16 v[0:3], v[176:179], v[210:213], v[0:3]
	v_mfma_f32_16x16x32_bf16 v[52:55], v[172:175], v[190:193], v[52:55]
	v_mfma_f32_16x16x32_bf16 v[48:51], v[182:185], v[190:193], v[48:51]
	v_mfma_f32_16x16x32_bf16 v[36:39], v[172:175], v[198:201], v[36:39]
	v_mfma_f32_16x16x32_bf16 v[32:35], v[182:185], v[198:201], v[32:35]
	v_mfma_f32_16x16x32_bf16 v[20:23], v[172:175], v[206:209], v[20:23]
	v_mfma_f32_16x16x32_bf16 v[16:19], v[182:185], v[206:209], v[16:19]
	v_mfma_f32_16x16x32_bf16 v[4:7], v[172:175], v[214:217], v[4:7]
	v_mfma_f32_16x16x32_bf16 v[0:3], v[182:185], v[214:217], v[0:3]
	s_setprio 0
	s_barrier
	s_add_i32 s65, s65, 2
	s_add_u32 s30, s30, 0x100
	s_addc_u32 s31, s31, 0
	s_add_u32 s63, s63, 0x100
	s_addc_u32 s64, s64, 0
	s_cmp_gt_u32 s65, 13
	s_cbranch_scc0 .LBB0_1482
.Lhk_join_7:
	s_and_b64 vcc, exec, s[20:21]
	s_cbranch_vccz .LBB0_1485
	s_barrier

.LBB0_1880:
	s_ashr_i32 s23, s22, 31
	s_lshl_b64 s[24:25], s[22:23], 19
	s_add_u32 s24, s36, s24
	s_addc_u32 s25, s37, s25
	s_and_b64 s[26:27], s[6:7], exec
	s_cselect_b32 s23, s25, s29
	s_cselect_b32 s56, s24, s28
	s_ashr_i32 s21, s20, 31
	s_lshl_b64 s[26:27], s[20:21], 19
	s_add_u32 s26, s38, s26
	s_addc_u32 s27, s39, s27
	s_and_b64 s[34:35], s[6:7], exec
	s_cselect_b32 s21, s27, s31
	s_cselect_b32 s57, s26, s30
	s_add_u32 s28, s28, 0x40080
	s_addc_u32 s29, s29, 0
	s_add_u32 s58, s30, 0x100
	v_mov_b32_e32 v0, 0
	s_addc_u32 s59, s31, 0
	s_mov_b32 s61, -2
	v_mov_b32_e32 v1, v0
	v_mov_b32_e32 v2, v0
	v_mov_b32_e32 v3, v0
	v_mov_b32_e32 v4, v0
	v_mov_b32_e32 v5, v0
	v_mov_b32_e32 v6, v0
	v_mov_b32_e32 v7, v0
	v_mov_b32_e32 v16, v0
	v_mov_b32_e32 v17, v0
	v_mov_b32_e32 v18, v0
	v_mov_b32_e32 v19, v0
	v_mov_b32_e32 v20, v0
	v_mov_b32_e32 v21, v0
	v_mov_b32_e32 v22, v0
	v_mov_b32_e32 v23, v0
	v_mov_b32_e32 v32, v0
	v_mov_b32_e32 v33, v0
	v_mov_b32_e32 v34, v0
	v_mov_b32_e32 v35, v0
	v_mov_b32_e32 v36, v0
	v_mov_b32_e32 v37, v0
	v_mov_b32_e32 v38, v0
	v_mov_b32_e32 v39, v0
	v_mov_b32_e32 v48, v0
	v_mov_b32_e32 v49, v0
	v_mov_b32_e32 v50, v0
	v_mov_b32_e32 v51, v0
	v_mov_b32_e32 v52, v0
	v_mov_b32_e32 v53, v0
	v_mov_b32_e32 v54, v0
	v_mov_b32_e32 v55, v0
	v_mov_b32_e32 v8, v0
	v_mov_b32_e32 v9, v0
	v_mov_b32_e32 v10, v0
	v_mov_b32_e32 v11, v0
	v_mov_b32_e32 v12, v0
	v_mov_b32_e32 v13, v0
	v_mov_b32_e32 v14, v0
	v_mov_b32_e32 v15, v0
	v_mov_b32_e32 v24, v0
	v_mov_b32_e32 v25, v0
	v_mov_b32_e32 v26, v0
	v_mov_b32_e32 v27, v0
	v_mov_b32_e32 v28, v0
	v_mov_b32_e32 v29, v0
	v_mov_b32_e32 v30, v0
	v_mov_b32_e32 v31, v0
	v_mov_b32_e32 v40, v0
	v_mov_b32_e32 v41, v0
	v_mov_b32_e32 v42, v0
	v_mov_b32_e32 v43, v0
	v_mov_b32_e32 v44, v0
	v_mov_b32_e32 v45, v0
	v_mov_b32_e32 v46, v0
	v_mov_b32_e32 v47, v0
	v_mov_b32_e32 v56, v0
	v_mov_b32_e32 v57, v0
	v_mov_b32_e32 v58, v0
	v_mov_b32_e32 v59, v0
	v_mov_b32_e32 v60, v0
	v_mov_b32_e32 v61, v0
	v_mov_b32_e32 v62, v0
	v_mov_b32_e32 v63, v0
	v_mov_b32_e32 v64, v0
	v_mov_b32_e32 v65, v0
	v_mov_b32_e32 v66, v0
	v_mov_b32_e32 v67, v0
	v_mov_b32_e32 v68, v0
	v_mov_b32_e32 v69, v0
	v_mov_b32_e32 v70, v0
	v_mov_b32_e32 v71, v0
	v_mov_b32_e32 v80, v0
	v_mov_b32_e32 v81, v0
	v_mov_b32_e32 v82, v0
	v_mov_b32_e32 v83, v0
	v_mov_b32_e32 v84, v0
	v_mov_b32_e32 v85, v0
	v_mov_b32_e32 v86, v0
	v_mov_b32_e32 v87, v0
	v_mov_b32_e32 v96, v0
	v_mov_b32_e32 v97, v0
	v_mov_b32_e32 v98, v0
	v_mov_b32_e32 v99, v0
	v_mov_b32_e32 v100, v0
	v_mov_b32_e32 v101, v0
	v_mov_b32_e32 v102, v0
	v_mov_b32_e32 v103, v0
	v_mov_b32_e32 v112, v0
	v_mov_b32_e32 v113, v0
	v_mov_b32_e32 v114, v0
	v_mov_b32_e32 v115, v0
	v_mov_b32_e32 v116, v0
	v_mov_b32_e32 v117, v0
	v_mov_b32_e32 v118, v0
	v_mov_b32_e32 v119, v0
	v_mov_b32_e32 v72, v0
	v_mov_b32_e32 v73, v0
	v_mov_b32_e32 v74, v0
	v_mov_b32_e32 v75, v0
	v_mov_b32_e32 v76, v0
	v_mov_b32_e32 v77, v0
	v_mov_b32_e32 v78, v0
	v_mov_b32_e32 v79, v0
	v_mov_b32_e32 v88, v0
	v_mov_b32_e32 v89, v0
	v_mov_b32_e32 v90, v0
	v_mov_b32_e32 v91, v0
	v_mov_b32_e32 v92, v0
	v_mov_b32_e32 v93, v0
	v_mov_b32_e32 v94, v0
	v_mov_b32_e32 v95, v0
	v_mov_b32_e32 v104, v0
	v_mov_b32_e32 v105, v0
	v_mov_b32_e32 v106, v0
	v_mov_b32_e32 v107, v0
	v_mov_b32_e32 v108, v0
	v_mov_b32_e32 v109, v0
	v_mov_b32_e32 v110, v0
	v_mov_b32_e32 v111, v0
	v_mov_b32_e32 v120, v0
	v_mov_b32_e32 v121, v0
	v_mov_b32_e32 v122, v0
	v_mov_b32_e32 v123, v0
	v_mov_b32_e32 v124, v0
	v_mov_b32_e32 v125, v0
	v_mov_b32_e32 v126, v0
	v_mov_b32_e32 v127, v0
	s_branch .Lhk_skip_12

.Lmf_12_7:
	s_setprio 0
	s_barrier
	s_add_i32 s61, s61, 2
	s_add_u32 s28, s28, 0x100
	s_addc_u32 s29, s29, 0
	s_add_u32 s58, s58, 0x100
	s_addc_u32 s59, s59, 0
	s_cmp_gt_u32 s61, 13
	s_cbranch_scc0 .Lhk_12
	s_branch .Lhk_join_12
.Lhk_skip_12:
	s_bitcmp1_b32 s101, 6
	s_cbranch_scc1 .Lhk_12
.LBB0_1881:
	ds_read_b128 v[144:147], v155
	ds_read_b128 v[148:151], v155 offset:1024
	ds_read_b128 v[160:163], v155 offset:2048
	ds_read_b128 v[164:167], v155 offset:3072
	ds_read_b128 v[168:171], v156
	ds_read_b128 v[172:175], v156 offset:1024
	ds_read_b128 v[176:179], v156 offset:2048
	ds_read_b128 v[182:185], v156 offset:3072
	s_add_u32 s30, s28, 0xfffc0080
	s_addc_u32 s31, s29, -1
	s_cmp_eq_u32 s61, 12
	s_cselect_b32 s35, s23, s31
	s_cselect_b32 s34, s56, s30
	s_cselect_b32 s31, s21, s59
	s_cselect_b32 s30, s57, s58
	v_lshl_add_u64 v[152:153], s[28:29], 0, v[136:137]
	s_add_i32 m0, s41, 0xc000
	ds_read_b128 v[186:189], v157
	ds_read_b128 v[190:193], v157 offset:1024
	ds_read_b128 v[194:197], v157 offset:2048
	ds_read_b128 v[198:201], v157 offset:3072
	ds_read_b128 v[202:205], v157 offset:4096
	ds_read_b128 v[206:209], v157 offset:5120
	ds_read_b128 v[210:213], v157 offset:6144
	ds_read_b128 v[214:217], v157 offset:7168
	global_load_lds_dwordx4 v[152:153], off
	v_lshl_add_u64 v[152:153], s[28:29], 0, v[138:139]
	s_add_i32 m0, s41, 0xe000
	s_nop 0
	global_load_lds_dwordx4 v[152:153], off
	s_waitcnt vmcnt(8)
	s_waitcnt lgkmcnt(0)
	s_barrier
	s_setprio 1
	s_waitcnt lgkmcnt(0)
	v_mfma_f32_16x16x32_bf16 v[124:127], v[144:147], v[186:189], v[124:127]
	v_mfma_f32_16x16x32_bf16 v[120:123], v[160:163], v[186:189], v[120:123]
	v_mfma_f32_16x16x32_bf16 v[108:111], v[144:147], v[194:197], v[108:111]
	v_mfma_f32_16x16x32_bf16 v[104:107], v[160:163], v[194:197], v[104:107]
	v_mfma_f32_16x16x32_bf16 v[92:95], v[144:147], v[202:205], v[92:95]
	v_mfma_f32_16x16x32_bf16 v[88:91], v[160:163], v[202:205], v[88:91]
	v_mfma_f32_16x16x32_bf16 v[76:79], v[144:147], v[210:213], v[76:79]
	v_mfma_f32_16x16x32_bf16 v[72:75], v[160:163], v[210:213], v[72:75]
	v_mfma_f32_16x16x32_bf16 v[124:127], v[148:151], v[190:193], v[124:127]
	v_mfma_f32_16x16x32_bf16 v[120:123], v[164:167], v[190:193], v[120:123]
	v_mfma_f32_16x16x32_bf16 v[108:111], v[148:151], v[198:201], v[108:111]
	v_mfma_f32_16x16x32_bf16 v[104:107], v[164:167], v[198:201], v[104:107]
	v_mfma_f32_16x16x32_bf16 v[92:95], v[148:151], v[206:209], v[92:95]
	v_mfma_f32_16x16x32_bf16 v[88:91], v[164:167], v[206:209], v[88:91]
	v_mfma_f32_16x16x32_bf16 v[76:79], v[148:151], v[214:217], v[76:79]
	v_mfma_f32_16x16x32_bf16 v[72:75], v[164:167], v[214:217], v[72:75]
	s_setprio 0
	s_setprio 1
	v_mfma_f32_16x16x32_bf16 v[116:119], v[168:171], v[186:189], v[116:119]
	v_mfma_f32_16x16x32_bf16 v[112:115], v[176:179], v[186:189], v[112:115]
	v_mfma_f32_16x16x32_bf16 v[100:103], v[168:171], v[194:197], v[100:103]
	v_mfma_f32_16x16x32_bf16 v[96:99], v[176:179], v[194:197], v[96:99]
	v_mfma_f32_16x16x32_bf16 v[84:87], v[168:171], v[202:205], v[84:87]
	v_mfma_f32_16x16x32_bf16 v[80:83], v[176:179], v[202:205], v[80:83]
	v_mfma_f32_16x16x32_bf16 v[68:71], v[168:171], v[210:213], v[68:71]
	v_mfma_f32_16x16x32_bf16 v[64:67], v[176:179], v[210:213], v[64:67]
	v_mfma_f32_16x16x32_bf16 v[116:119], v[172:175], v[190:193], v[116:119]
	v_mfma_f32_16x16x32_bf16 v[112:115], v[182:185], v[190:193], v[112:115]
	v_mfma_f32_16x16x32_bf16 v[100:103], v[172:175], v[198:201], v[100:103]
	v_mfma_f32_16x16x32_bf16 v[96:99], v[182:185], v[198:201], v[96:99]
	v_mfma_f32_16x16x32_bf16 v[84:87], v[172:175], v[206:209], v[84:87]
	v_mfma_f32_16x16x32_bf16 v[80:83], v[182:185], v[206:209], v[80:83]
	v_mfma_f32_16x16x32_bf16 v[68:71], v[172:175], v[214:217], v[68:71]
	v_mfma_f32_16x16x32_bf16 v[64:67], v[182:185], v[214:217], v[64:67]
	s_setprio 0
	s_barrier
	s_add_i32 s62, s52, s40
	v_lshl_add_u64 v[152:153], s[30:31], 0, v[132:133]
	s_mov_b32 m0, s62
	ds_read_b128 v[186:189], v157 offset:16384
	ds_read_b128 v[190:193], v157 offset:17408
	ds_read_b128 v[194:197], v157 offset:18432
	ds_read_b128 v[198:201], v157 offset:19456
	ds_read_b128 v[202:205], v157 offset:20480
	ds_read_b128 v[206:209], v157 offset:21504
	ds_read_b128 v[210:213], v157 offset:22528
	ds_read_b128 v[214:217], v157 offset:23552
	global_load_lds_dwordx4 v[152:153], off
	s_add_i32 m0, s62, 0x2000
	s_add_u32 s62, s30, 0x40000
	v_lshl_add_u64 v[218:219], s[30:31], 0, v[128:129]
	s_addc_u32 s63, s31, 0
	s_add_i32 s64, s53, s40
	global_load_lds_dwordx4 v[218:219], off
	v_lshl_add_u64 v[220:221], s[62:63], 0, v[132:133]
	s_mov_b32 m0, s64
	v_lshl_add_u64 v[222:223], s[34:35], 0, v[130:131]
	global_load_lds_dwordx4 v[220:221], off
	v_lshl_add_u64 v[220:221], s[62:63], 0, v[128:129]
	s_add_i32 m0, s64, 0x2000
	s_nop 0
	global_load_lds_dwordx4 v[220:221], off
	v_lshl_add_u64 v[220:221], s[34:35], 0, v[134:135]
	s_mov_b32 m0, s41
	s_nop 0
	global_load_lds_dwordx4 v[220:221], off
	s_mov_b32 m0, s42
	s_nop 0
	global_load_lds_dwordx4 v[222:223], off
	s_waitcnt vmcnt(8)
	s_waitcnt lgkmcnt(0)
	s_barrier
	s_setprio 1
	s_waitcnt lgkmcnt(0)
	v_mfma_f32_16x16x32_bf16 v[60:63], v[144:147], v[186:189], v[60:63]
	v_mfma_f32_16x16x32_bf16 v[56:59], v[160:163], v[186:189], v[56:59]
	v_mfma_f32_16x16x32_bf16 v[44:47], v[144:147], v[194:197], v[44:47]
	v_mfma_f32_16x16x32_bf16 v[40:43], v[160:163], v[194:197], v[40:43]
	v_mfma_f32_16x16x32_bf16 v[28:31], v[144:147], v[202:205], v[28:31]
	v_mfma_f32_16x16x32_bf16 v[24:27], v[160:163], v[202:205], v[24:27]
	v_mfma_f32_16x16x32_bf16 v[12:15], v[144:147], v[210:213], v[12:15]
	v_mfma_f32_16x16x32_bf16 v[8:11], v[160:163], v[210:213], v[8:11]
	v_mfma_f32_16x16x32_bf16 v[60:63], v[148:151], v[190:193], v[60:63]
	v_mfma_f32_16x16x32_bf16 v[56:59], v[164:167], v[190:193], v[56:59]
	v_mfma_f32_16x16x32_bf16 v[44:47], v[148:151], v[198:201], v[44:47]
	v_mfma_f32_16x16x32_bf16 v[40:43], v[164:167], v[198:201], v[40:43]
	v_mfma_f32_16x16x32_bf16 v[28:31], v[148:151], v[206:209], v[28:31]
	v_mfma_f32_16x16x32_bf16 v[24:27], v[164:167], v[206:209], v[24:27]
	v_mfma_f32_16x16x32_bf16 v[12:15], v[148:151], v[214:217], v[12:15]
	v_mfma_f32_16x16x32_bf16 v[8:11], v[164:167], v[214:217], v[8:11]
	s_setprio 0
	s_setprio 1
	v_mfma_f32_16x16x32_bf16 v[52:55], v[168:171], v[186:189], v[52:55]
	v_mfma_f32_16x16x32_bf16 v[48:51], v[176:179], v[186:189], v[48:51]
	v_mfma_f32_16x16x32_bf16 v[36:39], v[168:171], v[194:197], v[36:39]
	v_mfma_f32_16x16x32_bf16 v[32:35], v[176:179], v[194:197], v[32:35]
	v_mfma_f32_16x16x32_bf16 v[20:23], v[168:171], v[202:205], v[20:23]
	v_mfma_f32_16x16x32_bf16 v[16:19], v[176:179], v[202:205], v[16:19]
	v_mfma_f32_16x16x32_bf16 v[4:7], v[168:171], v[210:213], v[4:7]
	v_mfma_f32_16x16x32_bf16 v[0:3], v[176:179], v[210:213], v[0:3]
	v_mfma_f32_16x16x32_bf16 v[52:55], v[172:175], v[190:193], v[52:55]
	v_mfma_f32_16x16x32_bf16 v[48:51], v[182:185], v[190:193], v[48:51]
	v_mfma_f32_16x16x32_bf16 v[36:39], v[172:175], v[198:201], v[36:39]
	v_mfma_f32_16x16x32_bf16 v[32:35], v[182:185], v[198:201], v[32:35]
	v_mfma_f32_16x16x32_bf16 v[20:23], v[172:175], v[206:209], v[20:23]
	v_mfma_f32_16x16x32_bf16 v[16:19], v[182:185], v[206:209], v[16:19]
	v_mfma_f32_16x16x32_bf16 v[4:7], v[172:175], v[214:217], v[4:7]
	v_mfma_f32_16x16x32_bf16 v[0:3], v[182:185], v[214:217], v[0:3]
	s_setprio 0
	s_barrier
	s_add_i32 s62, 0, 0x18000
	v_add_u32_e32 v159, s62, v154
	s_add_i32 s63, 0, 0x1c000
	ds_read_b128 v[144:147], v159
	ds_read_b128 v[148:151], v159 offset:1024
	ds_read_b128 v[160:163], v159 offset:2048
	ds_read_b128 v[164:167], v159 offset:3072
	v_add_u32_e32 v159, s63, v154
	ds_read_b128 v[168:171], v159
	ds_read_b128 v[172:175], v159 offset:1024
	ds_read_b128 v[176:179], v159 offset:2048
	ds_read_b128 v[182:185], v159 offset:3072
	s_add_u32 s34, s34, 0x40000
	s_addc_u32 s35, s35, 0
	s_mov_b32 m0, s43
	v_lshl_add_u64 v[224:225], s[34:35], 0, v[134:135]
	ds_read_b128 v[186:189], v157 offset:32768
	ds_read_b128 v[190:193], v157 offset:33792
	ds_read_b128 v[194:197], v157 offset:34816
	ds_read_b128 v[198:201], v157 offset:35840
	ds_read_b128 v[202:205], v157 offset:36864
	ds_read_b128 v[206:209], v157 offset:37888
	ds_read_b128 v[210:213], v157 offset:38912
	ds_read_b128 v[214:217], v157 offset:39936
	global_load_lds_dwordx4 v[224:225], off
	v_lshl_add_u64 v[224:225], s[34:35], 0, v[130:131]
	s_mov_b32 m0, s44
	s_nop 0
	global_load_lds_dwordx4 v[224:225], off
	s_waitcnt vmcnt(8)
	s_waitcnt lgkmcnt(0)
	s_barrier
	s_setprio 1
	s_waitcnt lgkmcnt(0)
	v_mfma_f32_16x16x32_bf16 v[124:127], v[144:147], v[186:189], v[124:127]
	v_mfma_f32_16x16x32_bf16 v[120:123], v[160:163], v[186:189], v[120:123]
	v_mfma_f32_16x16x32_bf16 v[108:111], v[144:147], v[194:197], v[108:111]
	v_mfma_f32_16x16x32_bf16 v[104:107], v[160:163], v[194:197], v[104:107]
	v_mfma_f32_16x16x32_bf16 v[92:95], v[144:147], v[202:205], v[92:95]
	v_mfma_f32_16x16x32_bf16 v[88:91], v[160:163], v[202:205], v[88:91]
	v_mfma_f32_16x16x32_bf16 v[76:79], v[144:147], v[210:213], v[76:79]
	v_mfma_f32_16x16x32_bf16 v[72:75], v[160:163], v[210:213], v[72:75]
	v_mfma_f32_16x16x32_bf16 v[124:127], v[148:151], v[190:193], v[124:127]
	v_mfma_f32_16x16x32_bf16 v[120:123], v[164:167], v[190:193], v[120:123]
	v_mfma_f32_16x16x32_bf16 v[108:111], v[148:151], v[198:201], v[108:111]
	v_mfma_f32_16x16x32_bf16 v[104:107], v[164:167], v[198:201], v[104:107]
	v_mfma_f32_16x16x32_bf16 v[92:95], v[148:151], v[206:209], v[92:95]
	v_mfma_f32_16x16x32_bf16 v[88:91], v[164:167], v[206:209], v[88:91]
	v_mfma_f32_16x16x32_bf16 v[76:79], v[148:151], v[214:217], v[76:79]
	v_mfma_f32_16x16x32_bf16 v[72:75], v[164:167], v[214:217], v[72:75]
	s_setprio 0
	s_setprio 1
	v_mfma_f32_16x16x32_bf16 v[116:119], v[168:171], v[186:189], v[116:119]
	v_mfma_f32_16x16x32_bf16 v[112:115], v[176:179], v[186:189], v[112:115]
	v_mfma_f32_16x16x32_bf16 v[100:103], v[168:171], v[194:197], v[100:103]
	v_mfma_f32_16x16x32_bf16 v[96:99], v[176:179], v[194:197], v[96:99]
	v_mfma_f32_16x16x32_bf16 v[84:87], v[168:171], v[202:205], v[84:87]
	v_mfma_f32_16x16x32_bf16 v[80:83], v[176:179], v[202:205], v[80:83]
	v_mfma_f32_16x16x32_bf16 v[68:71], v[168:171], v[210:213], v[68:71]
	v_mfma_f32_16x16x32_bf16 v[64:67], v[176:179], v[210:213], v[64:67]
	v_mfma_f32_16x16x32_bf16 v[116:119], v[172:175], v[190:193], v[116:119]
	v_mfma_f32_16x16x32_bf16 v[112:115], v[182:185], v[190:193], v[112:115]
	v_mfma_f32_16x16x32_bf16 v[100:103], v[172:175], v[198:201], v[100:103]
	v_mfma_f32_16x16x32_bf16 v[96:99], v[182:185], v[198:201], v[96:99]
	v_mfma_f32_16x16x32_bf16 v[84:87], v[172:175], v[206:209], v[84:87]
	v_mfma_f32_16x16x32_bf16 v[80:83], v[182:185], v[206:209], v[80:83]
	v_mfma_f32_16x16x32_bf16 v[68:71], v[172:175], v[214:217], v[68:71]
	v_mfma_f32_16x16x32_bf16 v[64:67], v[182:185], v[214:217], v[64:67]
	s_setprio 0
	s_barrier
	s_add_i32 s34, s62, s40
	v_lshl_add_u64 v[152:153], v[152:153], 0, s[16:17]
	s_mov_b32 m0, s34
	ds_read_b128 v[186:189], v157 offset:49152
	ds_read_b128 v[190:193], v157 offset:50176
	ds_read_b128 v[194:197], v157 offset:51200
	ds_read_b128 v[198:201], v157 offset:52224
	ds_read_b128 v[202:205], v157 offset:53248
	ds_read_b128 v[206:209], v157 offset:54272
	ds_read_b128 v[210:213], v157 offset:55296
	ds_read_b128 v[214:217], v157 offset:56320
	global_load_lds_dwordx4 v[152:153], off
	s_add_i32 m0, s34, 0x2000
	s_add_u32 s30, s30, 0x40080
	v_lshl_add_u64 v[152:153], v[218:219], 0, s[16:17]
	s_addc_u32 s31, s31, 0
	s_add_i32 s34, s63, s40
	global_load_lds_dwordx4 v[152:153], off
	v_lshl_add_u64 v[152:153], s[30:31], 0, v[132:133]
	s_mov_b32 m0, s34
	s_nop 0
	global_load_lds_dwordx4 v[152:153], off
	v_lshl_add_u64 v[152:153], s[30:31], 0, v[128:129]
	s_add_i32 m0, s34, 0x2000
	s_nop 0
	global_load_lds_dwordx4 v[152:153], off
	v_lshl_add_u64 v[152:153], v[220:221], 0, s[16:17]
	s_mov_b32 m0, s50
	s_nop 0
	global_load_lds_dwordx4 v[152:153], off
	v_lshl_add_u64 v[152:153], v[222:223], 0, s[16:17]
	s_mov_b32 m0, s51
	s_nop 0
	global_load_lds_dwordx4 v[152:153], off
	s_waitcnt vmcnt(8)
	s_waitcnt lgkmcnt(0)
	s_barrier
	s_setprio 1
	s_waitcnt lgkmcnt(0)
	v_mfma_f32_16x16x32_bf16 v[60:63], v[144:147], v[186:189], v[60:63]
	v_mfma_f32_16x16x32_bf16 v[56:59], v[160:163], v[186:189], v[56:59]
	v_mfma_f32_16x16x32_bf16 v[44:47], v[144:147], v[194:197], v[44:47]
	v_mfma_f32_16x16x32_bf16 v[40:43], v[160:163], v[194:197], v[40:43]
	v_mfma_f32_16x16x32_bf16 v[28:31], v[144:147], v[202:205], v[28:31]
	v_mfma_f32_16x16x32_bf16 v[24:27], v[160:163], v[202:205], v[24:27]
	v_mfma_f32_16x16x32_bf16 v[12:15], v[144:147], v[210:213], v[12:15]
	v_mfma_f32_16x16x32_bf16 v[8:11], v[160:163], v[210:213], v[8:11]
	v_mfma_f32_16x16x32_bf16 v[60:63], v[148:151], v[190:193], v[60:63]
	v_mfma_f32_16x16x32_bf16 v[56:59], v[164:167], v[190:193], v[56:59]
	v_mfma_f32_16x16x32_bf16 v[44:47], v[148:151], v[198:201], v[44:47]
	v_mfma_f32_16x16x32_bf16 v[40:43], v[164:167], v[198:201], v[40:43]
	v_mfma_f32_16x16x32_bf16 v[28:31], v[148:151], v[206:209], v[28:31]
	v_mfma_f32_16x16x32_bf16 v[24:27], v[164:167], v[206:209], v[24:27]
	v_mfma_f32_16x16x32_bf16 v[12:15], v[148:151], v[214:217], v[12:15]
	v_mfma_f32_16x16x32_bf16 v[8:11], v[164:167], v[214:217], v[8:11]
	s_setprio 0
	s_setprio 1
	v_mfma_f32_16x16x32_bf16 v[52:55], v[168:171], v[186:189], v[52:55]
	v_mfma_f32_16x16x32_bf16 v[48:51], v[176:179], v[186:189], v[48:51]
	v_mfma_f32_16x16x32_bf16 v[36:39], v[168:171], v[194:197], v[36:39]
	v_mfma_f32_16x16x32_bf16 v[32:35], v[176:179], v[194:197], v[32:35]
	v_mfma_f32_16x16x32_bf16 v[20:23], v[168:171], v[202:205], v[20:23]
	v_mfma_f32_16x16x32_bf16 v[16:19], v[176:179], v[202:205], v[16:19]
	v_mfma_f32_16x16x32_bf16 v[4:7], v[168:171], v[210:213], v[4:7]
	v_mfma_f32_16x16x32_bf16 v[0:3], v[176:179], v[210:213], v[0:3]
	v_mfma_f32_16x16x32_bf16 v[52:55], v[172:175], v[190:193], v[52:55]
	v_mfma_f32_16x16x32_bf16 v[48:51], v[182:185], v[190:193], v[48:51]
	v_mfma_f32_16x16x32_bf16 v[36:39], v[172:175], v[198:201], v[36:39]
	v_mfma_f32_16x16x32_bf16 v[32:35], v[182:185], v[198:201], v[32:35]
	v_mfma_f32_16x16x32_bf16 v[20:23], v[172:175], v[206:209], v[20:23]
	v_mfma_f32_16x16x32_bf16 v[16:19], v[182:185], v[206:209], v[16:19]
	v_mfma_f32_16x16x32_bf16 v[4:7], v[172:175], v[214:217], v[4:7]
	v_mfma_f32_16x16x32_bf16 v[0:3], v[182:185], v[214:217], v[0:3]
	s_setprio 0
	s_barrier
	s_add_i32 s61, s61, 2
	s_add_u32 s28, s28, 0x100
	s_addc_u32 s29, s29, 0
	s_add_u32 s58, s58, 0x100
	s_addc_u32 s59, s59, 0
	s_cmp_gt_u32 s61, 13
	s_cbranch_scc0 .LBB0_1881
.Lhk_join_12:
	s_and_b64 vcc, exec, s[18:19]
	s_cbranch_vccz .LBB0_1884
	s_barrier
